# HGRN-in sample-row GEMM: LDS-DMA staged 64x128 tile (5-stage ring) replaces direct-from-global small_gemm + per-element branchy epilogue
# speedup vs baseline: 1.0255x; 1.0255x over previous
; template <int WM, int WN, int NT, class F>
; __device__ __forceinline__ void small_gemm(const bf16_t* A, int lda, const bf16_t* Bt, int ldb, int K, int N, int a_grp_cols, int bx, int G, int tid, const F& f) {
;     ...
;     const int lane = tid & 63, w = __builtin_amdgcn_readfirstlane(tid >> 6), c = lane & 15, g = lane >> 4, wm = w / WN, wn = w % WN;
;     constexpr int TM = 16 * WM, TN = 16 * NT * WN;
;     const int ntn = N / TN, ntiles = (MS / TM) * ntn;
;     for (int t = bx; t < ntiles; t += G) {
;         const int row0 = MP + (t / ntn) * TM + wm * 16, n0 = (t % ntn) * TN + wn * 16 * NT;
;         const bf16_t* ap = A + (size_t)(row0 + c) * lda + (n0 >> 8) * a_grp_cols + 8 * g;
;         const bf16_t* bp = Bt + (size_t)(n0 + c) * ldb + 8 * g;
;         f32x4 acc[NT];
; #pragma unroll
;         for (int nt = 0; nt < NT; ++nt) acc[nt] = (f32x4){0.f, 0.f, 0.f, 0.f};
; #pragma unroll 8
;         for (int k0 = 0; k0 < K; k0 += 32) { const bf16x8 av = *(const bf16x8*)(ap + k0);
; #pragma unroll
;             for (int nt = 0; nt < NT; ++nt) { const bf16x8 bv = *(const bf16x8*)(bp + (size_t)nt * 16 * ldb + k0); acc[nt] = __builtin_amdgcn_mfma_f32_16x16x32_bf16(av, bv, acc[nt], 0, 0, 0); } }
.LBB0_1032:
	s_or_b64 exec, exec, s[6:7]
	v_readlane_b32 s0, v235, 5
	v_mov_b32_e32 v32, v208
	v_readlane_b32 s1, v235, 6
	s_waitcnt lgkmcnt(0)
	s_barrier
	s_load_dwordx2 s[6:7], s[0:1], 0xa0
	s_load_dwordx2 s[16:17], s[0:1], 0x60
	v_readfirstlane_b32 s0, v32
	v_and_b32_e32 v33, 15, v32
	s_waitcnt lgkmcnt(0)
	s_add_u32 s18, s6, 0x9900000
	s_addc_u32 s19, s7, 0
	s_add_u32 s20, s6, 0xba00000
	s_addc_u32 s21, s7, 0
	s_add_u32 s22, s6, 0x3600000
	s_addc_u32 s23, s7, 0
	s_and_b64 vcc, exec, s[88:89]
	s_cbranch_vccnz .LBB0_1229
	s_lshr_b32 s0, s0, 6
	v_and_b32_e32 v0, 63, v32
	v_and_b32_e32 v1, 7, v0
	v_lshrrev_b32_e32 v2, 3, v0
	v_lshlrev_b32_e32 v4, 11, v1
	v_lshl_add_u32 v4, v2, 4, v4
	v_mov_b32_e32 v5, 0
	v_and_b32_e32 v1, 15, v0
	v_lshrrev_b32_e32 v2, 4, v0
	v_lshrrev_b32_e32 v22, 3, v1
	v_and_b32_e32 v23, 7, v1
	v_lshlrev_b32_e32 v22, 10, v22
	v_lshl_add_u32 v22, v2, 7, v22
	v_lshl_add_u32 v22, v23, 4, v22
	s_lshr_b32 s1, s0, 1
	s_and_b32 s27, s0, 1
	s_lshl_b32 s24, s1, 11
	s_lshl_b32 s25, s27, 13
	s_add_i32 s25, s25, 0x2000
	v_add_u32_e32 v12, s24, v22
	v_add_u32_e32 v17, s25, v22
	v_add_u32_e32 v13, s24, v22
	v_add_u32_e32 v18, s25, v22
	v_add_u32_e32 v14, s24, v22
	v_add_u32_e32 v19, s25, v22
	v_add_u32_e32 v15, s24, v22
	v_add_u32_e32 v20, s25, v22
	v_add_u32_e32 v16, s24, v22
	v_add_u32_e32 v21, s25, v22
	v_add_u32_e32 v13, 24576, v13
	v_add_u32_e32 v18, 24576, v18
	v_add_u32_e32 v14, 49152, v14
	v_add_u32_e32 v19, 49152, v19
	v_add_u32_e32 v15, 73728, v15
	v_add_u32_e32 v20, 73728, v20
	v_add_u32_e32 v16, 98304, v16
	v_add_u32_e32 v21, 98304, v21
	s_lshl_b32 s33, s1, 4
	v_lshl_add_u32 v34, v2, 2, s33
	v_lshlrev_b32_e32 v34, 11, v34
	s_lshl_b32 s33, s27, 6
	v_add_u32_e32 v35, s33, v1
	v_lshl_add_u32 v34, v35, 1, v34
	v_lshlrev_b32_e32 v86, 2, v35
	v_mov_b32_e32 v35, 0
	s_lshl_b32 s24, s0, 10
	s_lshl_b32 s25, s0, 11
	s_add_i32 s25, s25, 0x2000
	s_mov_b32 s4, 0x80
	s_mov_b32 s5, 0
	s_movk_i32 s3, 0x7fff
	s_mov_b32 s35, s2
.Lsg_hin_tile:
	s_lshr_b32 s1, s35, 5
	s_and_b32 s27, s35, 31
	s_lshl_b32 s1, s1, 6
	s_add_i32 s1, s1, 0x4000
	s_lshr_b32 s36, s27, 3
	s_lshl_b32 s33, s0, 3
	s_add_i32 s33, s33, s1
	s_lshl_b32 s33, s33, 11
	s_add_u32 s10, s6, s33
	s_addc_u32 s11, s7, 0
	s_add_u32 s10, s10, 0x7800000
	s_addc_u32 s11, s11, 0
	v_lshl_add_u64 v[6:7], s[10:11], 0, v[4:5]
	s_lshl_b32 s33, s27, 7
	s_lshl_b32 s34, s0, 4
	s_add_i32 s33, s33, s34
	s_lshl_b32 s33, s33, 11
	s_add_u32 s10, s6, s33
	s_addc_u32 s11, s7, 0
	s_add_u32 s10, s10, 0x2280000
	s_addc_u32 s11, s11, 0
	v_lshl_add_u64 v[8:9], s[10:11], 0, v[4:5]
	s_add_u32 s10, s10, 0x4000
	s_addc_u32 s11, s11, 0
	v_lshl_add_u64 v[10:11], s[10:11], 0, v[4:5]
	s_and_b32 s33, s35, 7
	s_lshl_b32 s34, s33, 9
	v_add_u32_e32 v1, s34, v86
	v_add_u32_e32 v2, 0x1000, v1
	s_waitcnt vmcnt(0)
	global_load_dword v128, v1, s[16:17] offset:0
	global_load_dword v132, v2, s[16:17] offset:0
	global_load_dword v129, v1, s[16:17] offset:64
	global_load_dword v133, v2, s[16:17] offset:64
	global_load_dword v130, v1, s[16:17] offset:128
	global_load_dword v134, v2, s[16:17] offset:128
	global_load_dword v131, v1, s[16:17] offset:192
	global_load_dword v135, v2, s[16:17] offset:192
	v_mov_b32_e32 v24, 0
	v_mov_b32_e32 v25, 0
	v_mov_b32_e32 v26, 0
	v_mov_b32_e32 v27, 0
	v_mov_b32_e32 v28, 0
	v_mov_b32_e32 v29, 0
	v_mov_b32_e32 v30, 0
	v_mov_b32_e32 v31, 0
	v_mov_b32_e32 v36, 0
	v_mov_b32_e32 v37, 0
	v_mov_b32_e32 v38, 0
	v_mov_b32_e32 v39, 0
	v_mov_b32_e32 v40, 0
	v_mov_b32_e32 v41, 0
	v_mov_b32_e32 v42, 0
	v_mov_b32_e32 v43, 0
	s_add_i32 m0, s24, 0
	s_nop 0
	global_load_lds_dwordx4 v[6:7], off
	v_lshl_add_u64 v[6:7], v[6:7], 0, s[4:5]
	s_add_i32 m0, s25, 0
	s_nop 0
	global_load_lds_dwordx4 v[8:9], off
	v_lshl_add_u64 v[8:9], v[8:9], 0, s[4:5]
	s_add_i32 m0, s25, 1024
	s_nop 0
	global_load_lds_dwordx4 v[10:11], off
	v_lshl_add_u64 v[10:11], v[10:11], 0, s[4:5]
	s_add_i32 m0, s24, 24576
	s_nop 0
	global_load_lds_dwordx4 v[6:7], off
	v_lshl_add_u64 v[6:7], v[6:7], 0, s[4:5]
	s_add_i32 m0, s25, 24576
	s_nop 0
	global_load_lds_dwordx4 v[8:9], off
	v_lshl_add_u64 v[8:9], v[8:9], 0, s[4:5]
	s_add_i32 m0, s25, 25600
	s_nop 0
	global_load_lds_dwordx4 v[10:11], off
	v_lshl_add_u64 v[10:11], v[10:11], 0, s[4:5]
	s_add_i32 m0, s24, 49152
	s_nop 0
	global_load_lds_dwordx4 v[6:7], off
	v_lshl_add_u64 v[6:7], v[6:7], 0, s[4:5]
	s_add_i32 m0, s25, 49152
	s_nop 0
	global_load_lds_dwordx4 v[8:9], off
	v_lshl_add_u64 v[8:9], v[8:9], 0, s[4:5]
	s_add_i32 m0, s25, 50176
	s_nop 0
	global_load_lds_dwordx4 v[10:11], off
	v_lshl_add_u64 v[10:11], v[10:11], 0, s[4:5]
	s_add_i32 m0, s24, 73728
	s_nop 0
	global_load_lds_dwordx4 v[6:7], off
	v_lshl_add_u64 v[6:7], v[6:7], 0, s[4:5]
	s_add_i32 m0, s25, 73728
	s_nop 0
	global_load_lds_dwordx4 v[8:9], off
	v_lshl_add_u64 v[8:9], v[8:9], 0, s[4:5]
	s_add_i32 m0, s25, 74752
	s_nop 0
	global_load_lds_dwordx4 v[10:11], off
	v_lshl_add_u64 v[10:11], v[10:11], 0, s[4:5]
	s_waitcnt vmcnt(9)
	s_barrier
	ds_read_b128 v[44:47], v12
	ds_read_b128 v[52:55], v17 offset:0
	ds_read_b128 v[60:63], v17 offset:2048
	ds_read_b128 v[68:71], v17 offset:4096
	ds_read_b128 v[76:79], v17 offset:6144
	ds_read_b128 v[48:51], v12 offset:512
	ds_read_b128 v[56:59], v17 offset:512
	ds_read_b128 v[64:67], v17 offset:2560
	ds_read_b128 v[72:75], v17 offset:4608
	ds_read_b128 v[80:83], v17 offset:6656
	s_add_i32 m0, s24, 98304
	s_nop 0
	global_load_lds_dwordx4 v[6:7], off
	v_lshl_add_u64 v[6:7], v[6:7], 0, s[4:5]
	s_add_i32 m0, s25, 98304
	s_nop 0
	global_load_lds_dwordx4 v[8:9], off
	v_lshl_add_u64 v[8:9], v[8:9], 0, s[4:5]
	s_add_i32 m0, s25, 99328
	s_nop 0
	global_load_lds_dwordx4 v[10:11], off
	v_lshl_add_u64 v[10:11], v[10:11], 0, s[4:5]
	s_waitcnt lgkmcnt(5)
	v_mfma_f32_16x16x32_bf16 v[24:27], v[44:47], v[52:55], v[24:27]
	v_mfma_f32_16x16x32_bf16 v[28:31], v[44:47], v[60:63], v[28:31]
	v_mfma_f32_16x16x32_bf16 v[36:39], v[44:47], v[68:71], v[36:39]
	v_mfma_f32_16x16x32_bf16 v[40:43], v[44:47], v[76:79], v[40:43]
	s_waitcnt lgkmcnt(0)
	v_mfma_f32_16x16x32_bf16 v[24:27], v[48:51], v[56:59], v[24:27]
	v_mfma_f32_16x16x32_bf16 v[28:31], v[48:51], v[64:67], v[28:31]
	v_mfma_f32_16x16x32_bf16 v[36:39], v[48:51], v[72:75], v[36:39]
	v_mfma_f32_16x16x32_bf16 v[40:43], v[48:51], v[80:83], v[40:43]
	s_waitcnt vmcnt(9)
	s_barrier
; template <int WM, int WN, int NT, class F>
; __device__ __forceinline__ void small_gemm(const bf16_t* A, int lda, const bf16_t* Bt, int ldb, int K, int N, int a_grp_cols, int bx, int G, int tid, const F& f) {
;     ...
; #pragma unroll 8
;         for (int k0 = 0; k0 < K; k0 += 32) { const bf16x8 av = *(const bf16x8*)(ap + k0);
; #pragma unroll
;             for (int nt = 0; nt < NT; ++nt) { const bf16x8 bv = *(const bf16x8*)(bp + (size_t)nt * 16 * ldb + k0); acc[nt] = __builtin_amdgcn_mfma_f32_16x16x32_bf16(av, bv, acc[nt], 0, 0, 0); } }
	ds_read_b128 v[88:91], v13
	ds_read_b128 v[96:99], v18 offset:0
	ds_read_b128 v[104:107], v18 offset:2048
	ds_read_b128 v[112:115], v18 offset:4096
	ds_read_b128 v[120:123], v18 offset:6144
	ds_read_b128 v[92:95], v13 offset:512
	ds_read_b128 v[100:103], v18 offset:512
	ds_read_b128 v[108:111], v18 offset:2560
	ds_read_b128 v[116:119], v18 offset:4608
	ds_read_b128 v[124:127], v18 offset:6656
	s_add_i32 m0, s24, 0
	s_nop 0
	global_load_lds_dwordx4 v[6:7], off
	v_lshl_add_u64 v[6:7], v[6:7], 0, s[4:5]
	s_add_i32 m0, s25, 0
	s_nop 0
	global_load_lds_dwordx4 v[8:9], off
	v_lshl_add_u64 v[8:9], v[8:9], 0, s[4:5]
	s_add_i32 m0, s25, 1024
	s_nop 0
	global_load_lds_dwordx4 v[10:11], off
	v_lshl_add_u64 v[10:11], v[10:11], 0, s[4:5]
	s_waitcnt lgkmcnt(5)
	v_mfma_f32_16x16x32_bf16 v[24:27], v[88:91], v[96:99], v[24:27]
	v_mfma_f32_16x16x32_bf16 v[28:31], v[88:91], v[104:107], v[28:31]
	v_mfma_f32_16x16x32_bf16 v[36:39], v[88:91], v[112:115], v[36:39]
	v_mfma_f32_16x16x32_bf16 v[40:43], v[88:91], v[120:123], v[40:43]
	s_waitcnt lgkmcnt(0)
	v_mfma_f32_16x16x32_bf16 v[24:27], v[92:95], v[100:103], v[24:27]
	v_mfma_f32_16x16x32_bf16 v[28:31], v[92:95], v[108:111], v[28:31]
	v_mfma_f32_16x16x32_bf16 v[36:39], v[92:95], v[116:119], v[36:39]
	v_mfma_f32_16x16x32_bf16 v[40:43], v[92:95], v[124:127], v[40:43]
	s_waitcnt vmcnt(9)
	s_barrier
	ds_read_b128 v[44:47], v14
	ds_read_b128 v[52:55], v19 offset:0
	ds_read_b128 v[60:63], v19 offset:2048
	ds_read_b128 v[68:71], v19 offset:4096
	ds_read_b128 v[76:79], v19 offset:6144
	ds_read_b128 v[48:51], v14 offset:512
	ds_read_b128 v[56:59], v19 offset:512
	ds_read_b128 v[64:67], v19 offset:2560
	ds_read_b128 v[72:75], v19 offset:4608
	ds_read_b128 v[80:83], v19 offset:6656
	s_add_i32 m0, s24, 24576
	s_nop 0
	global_load_lds_dwordx4 v[6:7], off
	v_lshl_add_u64 v[6:7], v[6:7], 0, s[4:5]
	s_add_i32 m0, s25, 24576
	s_nop 0
	global_load_lds_dwordx4 v[8:9], off
	v_lshl_add_u64 v[8:9], v[8:9], 0, s[4:5]
	s_add_i32 m0, s25, 25600
	s_nop 0
	global_load_lds_dwordx4 v[10:11], off
	v_lshl_add_u64 v[10:11], v[10:11], 0, s[4:5]
	s_waitcnt lgkmcnt(5)
	v_mfma_f32_16x16x32_bf16 v[24:27], v[44:47], v[52:55], v[24:27]
	v_mfma_f32_16x16x32_bf16 v[28:31], v[44:47], v[60:63], v[28:31]
	v_mfma_f32_16x16x32_bf16 v[36:39], v[44:47], v[68:71], v[36:39]
	v_mfma_f32_16x16x32_bf16 v[40:43], v[44:47], v[76:79], v[40:43]
	s_waitcnt lgkmcnt(0)
	v_mfma_f32_16x16x32_bf16 v[24:27], v[48:51], v[56:59], v[24:27]
	v_mfma_f32_16x16x32_bf16 v[28:31], v[48:51], v[64:67], v[28:31]
	v_mfma_f32_16x16x32_bf16 v[36:39], v[48:51], v[72:75], v[36:39]
	v_mfma_f32_16x16x32_bf16 v[40:43], v[48:51], v[80:83], v[40:43]
	s_waitcnt vmcnt(9)
	s_barrier
	ds_read_b128 v[88:91], v15
	ds_read_b128 v[96:99], v20 offset:0
	ds_read_b128 v[104:107], v20 offset:2048
	ds_read_b128 v[112:115], v20 offset:4096
	ds_read_b128 v[120:123], v20 offset:6144
	ds_read_b128 v[92:95], v15 offset:512
	ds_read_b128 v[100:103], v20 offset:512
	ds_read_b128 v[108:111], v20 offset:2560
	ds_read_b128 v[116:119], v20 offset:4608
	ds_read_b128 v[124:127], v20 offset:6656
	s_add_i32 m0, s24, 49152
	s_nop 0
	global_load_lds_dwordx4 v[6:7], off
	v_lshl_add_u64 v[6:7], v[6:7], 0, s[4:5]
	s_add_i32 m0, s25, 49152
	s_nop 0
	global_load_lds_dwordx4 v[8:9], off
	v_lshl_add_u64 v[8:9], v[8:9], 0, s[4:5]
	s_add_i32 m0, s25, 50176
	s_nop 0
	global_load_lds_dwordx4 v[10:11], off
	v_lshl_add_u64 v[10:11], v[10:11], 0, s[4:5]
	s_waitcnt lgkmcnt(5)
	v_mfma_f32_16x16x32_bf16 v[24:27], v[88:91], v[96:99], v[24:27]
	v_mfma_f32_16x16x32_bf16 v[28:31], v[88:91], v[104:107], v[28:31]
	v_mfma_f32_16x16x32_bf16 v[36:39], v[88:91], v[112:115], v[36:39]
	v_mfma_f32_16x16x32_bf16 v[40:43], v[88:91], v[120:123], v[40:43]
	s_waitcnt lgkmcnt(0)
	v_mfma_f32_16x16x32_bf16 v[24:27], v[92:95], v[100:103], v[24:27]
	v_mfma_f32_16x16x32_bf16 v[28:31], v[92:95], v[108:111], v[28:31]
	v_mfma_f32_16x16x32_bf16 v[36:39], v[92:95], v[116:119], v[36:39]
	v_mfma_f32_16x16x32_bf16 v[40:43], v[92:95], v[124:127], v[40:43]
	s_waitcnt vmcnt(9)
	s_barrier
	ds_read_b128 v[44:47], v16
	ds_read_b128 v[52:55], v21 offset:0
	ds_read_b128 v[60:63], v21 offset:2048
	ds_read_b128 v[68:71], v21 offset:4096
	ds_read_b128 v[76:79], v21 offset:6144
	ds_read_b128 v[48:51], v16 offset:512
	ds_read_b128 v[56:59], v21 offset:512
	ds_read_b128 v[64:67], v21 offset:2560
	ds_read_b128 v[72:75], v21 offset:4608
	ds_read_b128 v[80:83], v21 offset:6656
	s_add_i32 m0, s24, 73728
	s_nop 0
	global_load_lds_dwordx4 v[6:7], off
	v_lshl_add_u64 v[6:7], v[6:7], 0, s[4:5]
	s_add_i32 m0, s25, 73728
	s_nop 0
	global_load_lds_dwordx4 v[8:9], off
	v_lshl_add_u64 v[8:9], v[8:9], 0, s[4:5]
	s_add_i32 m0, s25, 74752
	s_nop 0
	global_load_lds_dwordx4 v[10:11], off
	v_lshl_add_u64 v[10:11], v[10:11], 0, s[4:5]
	s_waitcnt lgkmcnt(5)
	v_mfma_f32_16x16x32_bf16 v[24:27], v[44:47], v[52:55], v[24:27]
	v_mfma_f32_16x16x32_bf16 v[28:31], v[44:47], v[60:63], v[28:31]
	v_mfma_f32_16x16x32_bf16 v[36:39], v[44:47], v[68:71], v[36:39]
	v_mfma_f32_16x16x32_bf16 v[40:43], v[44:47], v[76:79], v[40:43]
	s_waitcnt lgkmcnt(0)
	v_mfma_f32_16x16x32_bf16 v[24:27], v[48:51], v[56:59], v[24:27]
	v_mfma_f32_16x16x32_bf16 v[28:31], v[48:51], v[64:67], v[28:31]
	v_mfma_f32_16x16x32_bf16 v[36:39], v[48:51], v[72:75], v[36:39]
	v_mfma_f32_16x16x32_bf16 v[40:43], v[48:51], v[80:83], v[40:43]
	s_waitcnt vmcnt(9)
	s_barrier
; template <int WM, int WN, int NT, class F>
; __device__ __forceinline__ void small_gemm(const bf16_t* A, int lda, const bf16_t* Bt, int ldb, int K, int N, int a_grp_cols, int bx, int G, int tid, const F& f) {
;     ...
; #pragma unroll 8
;         for (int k0 = 0; k0 < K; k0 += 32) { const bf16x8 av = *(const bf16x8*)(ap + k0);
; #pragma unroll
;             for (int nt = 0; nt < NT; ++nt) { const bf16x8 bv = *(const bf16x8*)(bp + (size_t)nt * 16 * ldb + k0); acc[nt] = __builtin_amdgcn_mfma_f32_16x16x32_bf16(av, bv, acc[nt], 0, 0, 0); } }
	ds_read_b128 v[88:91], v12
	ds_read_b128 v[96:99], v17 offset:0
	ds_read_b128 v[104:107], v17 offset:2048
	ds_read_b128 v[112:115], v17 offset:4096
	ds_read_b128 v[120:123], v17 offset:6144
	ds_read_b128 v[92:95], v12 offset:512
	ds_read_b128 v[100:103], v17 offset:512
	ds_read_b128 v[108:111], v17 offset:2560
	ds_read_b128 v[116:119], v17 offset:4608
	ds_read_b128 v[124:127], v17 offset:6656
	s_add_i32 m0, s24, 98304
	s_nop 0
	global_load_lds_dwordx4 v[6:7], off
	v_lshl_add_u64 v[6:7], v[6:7], 0, s[4:5]
	s_add_i32 m0, s25, 98304
	s_nop 0
	global_load_lds_dwordx4 v[8:9], off
	v_lshl_add_u64 v[8:9], v[8:9], 0, s[4:5]
	s_add_i32 m0, s25, 99328
	s_nop 0
	global_load_lds_dwordx4 v[10:11], off
	v_lshl_add_u64 v[10:11], v[10:11], 0, s[4:5]
	s_waitcnt lgkmcnt(5)
	v_mfma_f32_16x16x32_bf16 v[24:27], v[88:91], v[96:99], v[24:27]
	v_mfma_f32_16x16x32_bf16 v[28:31], v[88:91], v[104:107], v[28:31]
	v_mfma_f32_16x16x32_bf16 v[36:39], v[88:91], v[112:115], v[36:39]
	v_mfma_f32_16x16x32_bf16 v[40:43], v[88:91], v[120:123], v[40:43]
	s_waitcnt lgkmcnt(0)
	v_mfma_f32_16x16x32_bf16 v[24:27], v[92:95], v[100:103], v[24:27]
	v_mfma_f32_16x16x32_bf16 v[28:31], v[92:95], v[108:111], v[28:31]
	v_mfma_f32_16x16x32_bf16 v[36:39], v[92:95], v[116:119], v[36:39]
	v_mfma_f32_16x16x32_bf16 v[40:43], v[92:95], v[124:127], v[40:43]
	s_waitcnt vmcnt(9)
	s_barrier
	ds_read_b128 v[44:47], v13
	ds_read_b128 v[52:55], v18 offset:0
	ds_read_b128 v[60:63], v18 offset:2048
	ds_read_b128 v[68:71], v18 offset:4096
	ds_read_b128 v[76:79], v18 offset:6144
	ds_read_b128 v[48:51], v13 offset:512
	ds_read_b128 v[56:59], v18 offset:512
	ds_read_b128 v[64:67], v18 offset:2560
	ds_read_b128 v[72:75], v18 offset:4608
	ds_read_b128 v[80:83], v18 offset:6656
	s_add_i32 m0, s24, 0
	s_nop 0
	global_load_lds_dwordx4 v[6:7], off
	v_lshl_add_u64 v[6:7], v[6:7], 0, s[4:5]
	s_add_i32 m0, s25, 0
	s_nop 0
	global_load_lds_dwordx4 v[8:9], off
	v_lshl_add_u64 v[8:9], v[8:9], 0, s[4:5]
	s_add_i32 m0, s25, 1024
	s_nop 0
	global_load_lds_dwordx4 v[10:11], off
	v_lshl_add_u64 v[10:11], v[10:11], 0, s[4:5]
	s_waitcnt lgkmcnt(5)
	v_mfma_f32_16x16x32_bf16 v[24:27], v[44:47], v[52:55], v[24:27]
	v_mfma_f32_16x16x32_bf16 v[28:31], v[44:47], v[60:63], v[28:31]
	v_mfma_f32_16x16x32_bf16 v[36:39], v[44:47], v[68:71], v[36:39]
	v_mfma_f32_16x16x32_bf16 v[40:43], v[44:47], v[76:79], v[40:43]
	s_waitcnt lgkmcnt(0)
	v_mfma_f32_16x16x32_bf16 v[24:27], v[48:51], v[56:59], v[24:27]
	v_mfma_f32_16x16x32_bf16 v[28:31], v[48:51], v[64:67], v[28:31]
	v_mfma_f32_16x16x32_bf16 v[36:39], v[48:51], v[72:75], v[36:39]
	v_mfma_f32_16x16x32_bf16 v[40:43], v[48:51], v[80:83], v[40:43]
	s_waitcnt vmcnt(9)
	s_barrier
	ds_read_b128 v[88:91], v14
	ds_read_b128 v[96:99], v19 offset:0
	ds_read_b128 v[104:107], v19 offset:2048
	ds_read_b128 v[112:115], v19 offset:4096
	ds_read_b128 v[120:123], v19 offset:6144
	ds_read_b128 v[92:95], v14 offset:512
	ds_read_b128 v[100:103], v19 offset:512
	ds_read_b128 v[108:111], v19 offset:2560
	ds_read_b128 v[116:119], v19 offset:4608
	ds_read_b128 v[124:127], v19 offset:6656
	s_add_i32 m0, s24, 24576
	s_nop 0
	global_load_lds_dwordx4 v[6:7], off
	v_lshl_add_u64 v[6:7], v[6:7], 0, s[4:5]
	s_add_i32 m0, s25, 24576
	s_nop 0
	global_load_lds_dwordx4 v[8:9], off
	v_lshl_add_u64 v[8:9], v[8:9], 0, s[4:5]
	s_add_i32 m0, s25, 25600
	s_nop 0
	global_load_lds_dwordx4 v[10:11], off
	v_lshl_add_u64 v[10:11], v[10:11], 0, s[4:5]
	s_waitcnt lgkmcnt(5)
	v_mfma_f32_16x16x32_bf16 v[24:27], v[88:91], v[96:99], v[24:27]
	v_mfma_f32_16x16x32_bf16 v[28:31], v[88:91], v[104:107], v[28:31]
	v_mfma_f32_16x16x32_bf16 v[36:39], v[88:91], v[112:115], v[36:39]
	v_mfma_f32_16x16x32_bf16 v[40:43], v[88:91], v[120:123], v[40:43]
	s_waitcnt lgkmcnt(0)
	v_mfma_f32_16x16x32_bf16 v[24:27], v[92:95], v[100:103], v[24:27]
	v_mfma_f32_16x16x32_bf16 v[28:31], v[92:95], v[108:111], v[28:31]
	v_mfma_f32_16x16x32_bf16 v[36:39], v[92:95], v[116:119], v[36:39]
	v_mfma_f32_16x16x32_bf16 v[40:43], v[92:95], v[124:127], v[40:43]
	s_waitcnt vmcnt(9)
	s_barrier
	ds_read_b128 v[44:47], v15
	ds_read_b128 v[52:55], v20 offset:0
	ds_read_b128 v[60:63], v20 offset:2048
	ds_read_b128 v[68:71], v20 offset:4096
	ds_read_b128 v[76:79], v20 offset:6144
	ds_read_b128 v[48:51], v15 offset:512
	ds_read_b128 v[56:59], v20 offset:512
	ds_read_b128 v[64:67], v20 offset:2560
	ds_read_b128 v[72:75], v20 offset:4608
	ds_read_b128 v[80:83], v20 offset:6656
	s_add_i32 m0, s24, 49152
	s_nop 0
	global_load_lds_dwordx4 v[6:7], off
	v_lshl_add_u64 v[6:7], v[6:7], 0, s[4:5]
	s_add_i32 m0, s25, 49152
	s_nop 0
	global_load_lds_dwordx4 v[8:9], off
	v_lshl_add_u64 v[8:9], v[8:9], 0, s[4:5]
	s_add_i32 m0, s25, 50176
	s_nop 0
	global_load_lds_dwordx4 v[10:11], off
	v_lshl_add_u64 v[10:11], v[10:11], 0, s[4:5]
	s_waitcnt lgkmcnt(5)
	v_mfma_f32_16x16x32_bf16 v[24:27], v[44:47], v[52:55], v[24:27]
	v_mfma_f32_16x16x32_bf16 v[28:31], v[44:47], v[60:63], v[28:31]
	v_mfma_f32_16x16x32_bf16 v[36:39], v[44:47], v[68:71], v[36:39]
	v_mfma_f32_16x16x32_bf16 v[40:43], v[44:47], v[76:79], v[40:43]
	s_waitcnt lgkmcnt(0)
	v_mfma_f32_16x16x32_bf16 v[24:27], v[48:51], v[56:59], v[24:27]
	v_mfma_f32_16x16x32_bf16 v[28:31], v[48:51], v[64:67], v[28:31]
	v_mfma_f32_16x16x32_bf16 v[36:39], v[48:51], v[72:75], v[36:39]
	v_mfma_f32_16x16x32_bf16 v[40:43], v[48:51], v[80:83], v[40:43]
	s_waitcnt vmcnt(9)
	s_barrier
; template <int WM, int WN, int NT, class F>
; __device__ __forceinline__ void small_gemm(const bf16_t* A, int lda, const bf16_t* Bt, int ldb, int K, int N, int a_grp_cols, int bx, int G, int tid, const F& f) {
;     ...
; #pragma unroll 8
;         for (int k0 = 0; k0 < K; k0 += 32) { const bf16x8 av = *(const bf16x8*)(ap + k0);
; #pragma unroll
;             for (int nt = 0; nt < NT; ++nt) { const bf16x8 bv = *(const bf16x8*)(bp + (size_t)nt * 16 * ldb + k0); acc[nt] = __builtin_amdgcn_mfma_f32_16x16x32_bf16(av, bv, acc[nt], 0, 0, 0); } }
	ds_read_b128 v[88:91], v16
	ds_read_b128 v[96:99], v21 offset:0
	ds_read_b128 v[104:107], v21 offset:2048
	ds_read_b128 v[112:115], v21 offset:4096
	ds_read_b128 v[120:123], v21 offset:6144
	ds_read_b128 v[92:95], v16 offset:512
	ds_read_b128 v[100:103], v21 offset:512
	ds_read_b128 v[108:111], v21 offset:2560
	ds_read_b128 v[116:119], v21 offset:4608
	ds_read_b128 v[124:127], v21 offset:6656
	s_add_i32 m0, s24, 73728
	s_nop 0
	global_load_lds_dwordx4 v[6:7], off
	v_lshl_add_u64 v[6:7], v[6:7], 0, s[4:5]
	s_add_i32 m0, s25, 73728
	s_nop 0
	global_load_lds_dwordx4 v[8:9], off
	v_lshl_add_u64 v[8:9], v[8:9], 0, s[4:5]
	s_add_i32 m0, s25, 74752
	s_nop 0
	global_load_lds_dwordx4 v[10:11], off
	v_lshl_add_u64 v[10:11], v[10:11], 0, s[4:5]
	s_waitcnt lgkmcnt(5)
	v_mfma_f32_16x16x32_bf16 v[24:27], v[88:91], v[96:99], v[24:27]
	v_mfma_f32_16x16x32_bf16 v[28:31], v[88:91], v[104:107], v[28:31]
	v_mfma_f32_16x16x32_bf16 v[36:39], v[88:91], v[112:115], v[36:39]
	v_mfma_f32_16x16x32_bf16 v[40:43], v[88:91], v[120:123], v[40:43]
	s_waitcnt lgkmcnt(0)
	v_mfma_f32_16x16x32_bf16 v[24:27], v[92:95], v[100:103], v[24:27]
	v_mfma_f32_16x16x32_bf16 v[28:31], v[92:95], v[108:111], v[28:31]
	v_mfma_f32_16x16x32_bf16 v[36:39], v[92:95], v[116:119], v[36:39]
	v_mfma_f32_16x16x32_bf16 v[40:43], v[92:95], v[124:127], v[40:43]
	s_waitcnt vmcnt(9)
	s_barrier
	ds_read_b128 v[44:47], v12
	ds_read_b128 v[52:55], v17 offset:0
	ds_read_b128 v[60:63], v17 offset:2048
	ds_read_b128 v[68:71], v17 offset:4096
	ds_read_b128 v[76:79], v17 offset:6144
	ds_read_b128 v[48:51], v12 offset:512
	ds_read_b128 v[56:59], v17 offset:512
	ds_read_b128 v[64:67], v17 offset:2560
	ds_read_b128 v[72:75], v17 offset:4608
	ds_read_b128 v[80:83], v17 offset:6656
	s_add_i32 m0, s24, 98304
	s_nop 0
	global_load_lds_dwordx4 v[6:7], off
	v_lshl_add_u64 v[6:7], v[6:7], 0, s[4:5]
	s_add_i32 m0, s25, 98304
	s_nop 0
	global_load_lds_dwordx4 v[8:9], off
	v_lshl_add_u64 v[8:9], v[8:9], 0, s[4:5]
	s_add_i32 m0, s25, 99328
	s_nop 0
	global_load_lds_dwordx4 v[10:11], off
	v_lshl_add_u64 v[10:11], v[10:11], 0, s[4:5]
	s_waitcnt lgkmcnt(5)
	v_mfma_f32_16x16x32_bf16 v[24:27], v[44:47], v[52:55], v[24:27]
	v_mfma_f32_16x16x32_bf16 v[28:31], v[44:47], v[60:63], v[28:31]
	v_mfma_f32_16x16x32_bf16 v[36:39], v[44:47], v[68:71], v[36:39]
	v_mfma_f32_16x16x32_bf16 v[40:43], v[44:47], v[76:79], v[40:43]
	s_waitcnt lgkmcnt(0)
	v_mfma_f32_16x16x32_bf16 v[24:27], v[48:51], v[56:59], v[24:27]
	v_mfma_f32_16x16x32_bf16 v[28:31], v[48:51], v[64:67], v[28:31]
	v_mfma_f32_16x16x32_bf16 v[36:39], v[48:51], v[72:75], v[36:39]
	v_mfma_f32_16x16x32_bf16 v[40:43], v[48:51], v[80:83], v[40:43]
	s_waitcnt vmcnt(9)
	s_barrier
	ds_read_b128 v[88:91], v13
	ds_read_b128 v[96:99], v18 offset:0
	ds_read_b128 v[104:107], v18 offset:2048
	ds_read_b128 v[112:115], v18 offset:4096
	ds_read_b128 v[120:123], v18 offset:6144
	ds_read_b128 v[92:95], v13 offset:512
	ds_read_b128 v[100:103], v18 offset:512
	ds_read_b128 v[108:111], v18 offset:2560
	ds_read_b128 v[116:119], v18 offset:4608
	ds_read_b128 v[124:127], v18 offset:6656
	s_add_i32 m0, s24, 0
	s_nop 0
	global_load_lds_dwordx4 v[6:7], off
	v_lshl_add_u64 v[6:7], v[6:7], 0, s[4:5]
	s_add_i32 m0, s25, 0
	s_nop 0
	global_load_lds_dwordx4 v[8:9], off
	v_lshl_add_u64 v[8:9], v[8:9], 0, s[4:5]
	s_add_i32 m0, s25, 1024
	s_nop 0
	global_load_lds_dwordx4 v[10:11], off
	v_lshl_add_u64 v[10:11], v[10:11], 0, s[4:5]
	s_waitcnt lgkmcnt(5)
	v_mfma_f32_16x16x32_bf16 v[24:27], v[88:91], v[96:99], v[24:27]
	v_mfma_f32_16x16x32_bf16 v[28:31], v[88:91], v[104:107], v[28:31]
	v_mfma_f32_16x16x32_bf16 v[36:39], v[88:91], v[112:115], v[36:39]
	v_mfma_f32_16x16x32_bf16 v[40:43], v[88:91], v[120:123], v[40:43]
	s_waitcnt lgkmcnt(0)
	v_mfma_f32_16x16x32_bf16 v[24:27], v[92:95], v[100:103], v[24:27]
	v_mfma_f32_16x16x32_bf16 v[28:31], v[92:95], v[108:111], v[28:31]
	v_mfma_f32_16x16x32_bf16 v[36:39], v[92:95], v[116:119], v[36:39]
	v_mfma_f32_16x16x32_bf16 v[40:43], v[92:95], v[124:127], v[40:43]
	s_waitcnt vmcnt(9)
	s_barrier
	ds_read_b128 v[44:47], v14
	ds_read_b128 v[52:55], v19 offset:0
	ds_read_b128 v[60:63], v19 offset:2048
	ds_read_b128 v[68:71], v19 offset:4096
	ds_read_b128 v[76:79], v19 offset:6144
	ds_read_b128 v[48:51], v14 offset:512
	ds_read_b128 v[56:59], v19 offset:512
	ds_read_b128 v[64:67], v19 offset:2560
	ds_read_b128 v[72:75], v19 offset:4608
	ds_read_b128 v[80:83], v19 offset:6656
	s_waitcnt lgkmcnt(5)
	v_mfma_f32_16x16x32_bf16 v[24:27], v[44:47], v[52:55], v[24:27]
	v_mfma_f32_16x16x32_bf16 v[28:31], v[44:47], v[60:63], v[28:31]
	v_mfma_f32_16x16x32_bf16 v[36:39], v[44:47], v[68:71], v[36:39]
	v_mfma_f32_16x16x32_bf16 v[40:43], v[44:47], v[76:79], v[40:43]
	s_waitcnt lgkmcnt(0)
	v_mfma_f32_16x16x32_bf16 v[24:27], v[48:51], v[56:59], v[24:27]
	v_mfma_f32_16x16x32_bf16 v[28:31], v[48:51], v[64:67], v[28:31]
	v_mfma_f32_16x16x32_bf16 v[36:39], v[48:51], v[72:75], v[36:39]
	v_mfma_f32_16x16x32_bf16 v[40:43], v[48:51], v[80:83], v[40:43]
	s_waitcnt vmcnt(6)
	s_barrier
	ds_read_b128 v[88:91], v15
	ds_read_b128 v[96:99], v20 offset:0
	ds_read_b128 v[104:107], v20 offset:2048
	ds_read_b128 v[112:115], v20 offset:4096
	ds_read_b128 v[120:123], v20 offset:6144
	ds_read_b128 v[92:95], v15 offset:512
	ds_read_b128 v[100:103], v20 offset:512
	ds_read_b128 v[108:111], v20 offset:2560
	ds_read_b128 v[116:119], v20 offset:4608
	ds_read_b128 v[124:127], v20 offset:6656
	s_waitcnt lgkmcnt(5)
	v_mfma_f32_16x16x32_bf16 v[24:27], v[88:91], v[96:99], v[24:27]
	v_mfma_f32_16x16x32_bf16 v[28:31], v[88:91], v[104:107], v[28:31]
	v_mfma_f32_16x16x32_bf16 v[36:39], v[88:91], v[112:115], v[36:39]
	v_mfma_f32_16x16x32_bf16 v[40:43], v[88:91], v[120:123], v[40:43]
	s_waitcnt lgkmcnt(0)
	v_mfma_f32_16x16x32_bf16 v[24:27], v[92:95], v[100:103], v[24:27]
	v_mfma_f32_16x16x32_bf16 v[28:31], v[92:95], v[108:111], v[28:31]
	v_mfma_f32_16x16x32_bf16 v[36:39], v[92:95], v[116:119], v[36:39]
	v_mfma_f32_16x16x32_bf16 v[40:43], v[92:95], v[124:127], v[40:43]
	s_waitcnt vmcnt(3)
	s_barrier
; template <int WM, int WN, int NT, class F>
; __device__ __forceinline__ void small_gemm(const bf16_t* A, int lda, const bf16_t* Bt, int ldb, int K, int N, int a_grp_cols, int bx, int G, int tid, const F& f) {
;     ...
;         for (int k0 = 0; k0 < K; k0 += 32) { const bf16x8 av = *(const bf16x8*)(ap + k0);
; #pragma unroll
;             for (int nt = 0; nt < NT; ++nt) { const bf16x8 bv = *(const bf16x8*)(bp + (size_t)nt * 16 * ldb + k0); acc[nt] = __builtin_amdgcn_mfma_f32_16x16x32_bf16(av, bv, acc[nt], 0, 0, 0); } }
; #pragma unroll
;         for (int nt = 0; nt < NT; ++nt)
; #pragma unroll
;             for (int j = 0; j < 4; ++j) f(row0 + 4 * g + j, n0 + 16 * nt + c, acc[nt][j]);
	ds_read_b128 v[44:47], v16
	ds_read_b128 v[52:55], v21 offset:0
	ds_read_b128 v[60:63], v21 offset:2048
	ds_read_b128 v[68:71], v21 offset:4096
	ds_read_b128 v[76:79], v21 offset:6144
	ds_read_b128 v[48:51], v16 offset:512
	ds_read_b128 v[56:59], v21 offset:512
	ds_read_b128 v[64:67], v21 offset:2560
	ds_read_b128 v[72:75], v21 offset:4608
	ds_read_b128 v[80:83], v21 offset:6656
	s_waitcnt lgkmcnt(5)
	v_mfma_f32_16x16x32_bf16 v[24:27], v[44:47], v[52:55], v[24:27]
	v_mfma_f32_16x16x32_bf16 v[28:31], v[44:47], v[60:63], v[28:31]
	v_mfma_f32_16x16x32_bf16 v[36:39], v[44:47], v[68:71], v[36:39]
	v_mfma_f32_16x16x32_bf16 v[40:43], v[44:47], v[76:79], v[40:43]
	s_waitcnt lgkmcnt(0)
	v_mfma_f32_16x16x32_bf16 v[24:27], v[48:51], v[56:59], v[24:27]
	v_mfma_f32_16x16x32_bf16 v[28:31], v[48:51], v[64:67], v[28:31]
	v_mfma_f32_16x16x32_bf16 v[36:39], v[48:51], v[72:75], v[36:39]
	v_mfma_f32_16x16x32_bf16 v[40:43], v[48:51], v[80:83], v[40:43]
	s_waitcnt vmcnt(0)
	s_barrier
	ds_read_b128 v[88:91], v12
	ds_read_b128 v[96:99], v17 offset:0
	ds_read_b128 v[104:107], v17 offset:2048
	ds_read_b128 v[112:115], v17 offset:4096
	ds_read_b128 v[120:123], v17 offset:6144
	ds_read_b128 v[92:95], v12 offset:512
	ds_read_b128 v[100:103], v17 offset:512
	ds_read_b128 v[108:111], v17 offset:2560
	ds_read_b128 v[116:119], v17 offset:4608
	ds_read_b128 v[124:127], v17 offset:6656
	s_waitcnt lgkmcnt(5)
	v_mfma_f32_16x16x32_bf16 v[24:27], v[88:91], v[96:99], v[24:27]
	v_mfma_f32_16x16x32_bf16 v[28:31], v[88:91], v[104:107], v[28:31]
	v_mfma_f32_16x16x32_bf16 v[36:39], v[88:91], v[112:115], v[36:39]
	v_mfma_f32_16x16x32_bf16 v[40:43], v[88:91], v[120:123], v[40:43]
	s_waitcnt lgkmcnt(0)
	v_mfma_f32_16x16x32_bf16 v[24:27], v[92:95], v[100:103], v[24:27]
	v_mfma_f32_16x16x32_bf16 v[28:31], v[92:95], v[108:111], v[28:31]
	v_mfma_f32_16x16x32_bf16 v[36:39], v[92:95], v[116:119], v[36:39]
	v_mfma_f32_16x16x32_bf16 v[40:43], v[92:95], v[124:127], v[40:43]
	s_barrier
	s_add_u32 s28, s6, 0xdb00000
	s_addc_u32 s29, s7, 0
	s_cmp_eq_u32 s36, 0
	s_cselect_b32 s28, s18, s28
	s_cselect_b32 s29, s19, s29
	s_cmp_eq_u32 s36, 1
	s_cselect_b32 s28, s20, s28
	s_cselect_b32 s29, s21, s29
	s_cmp_eq_u32 s36, 3
	s_cselect_b32 s28, s22, s28
	s_cselect_b32 s29, s23, s29
	s_lshl_b32 s33, s1, 11
	s_and_b32 s34, s35, 7
	s_lshl_b32 s34, s34, 8
	s_add_i32 s33, s33, s34
	s_add_u32 s28, s28, s33
	s_addc_u32 s29, s29, 0
	v_lshl_add_u64 v[136:137], s[28:29], 0, v[34:35]
	s_mov_b32 s30, 0x1000
	s_mov_b32 s31, 0
	v_lshl_add_u64 v[138:139], v[136:137], 0, s[30:31]
	s_cmp_eq_u32 s36, 2
	s_cbranch_scc1 .Lsg_hin_st
	s_cmp_eq_u32 s36, 1
	s_cbranch_scc1 .Lsg_hin_k
	v_mul_f32_e32 v140, 0xbfb8aa3b, v24
	v_mul_f32_e32 v141, 0xbfb8aa3b, v25
	v_mul_f32_e32 v142, 0xbfb8aa3b, v26
	v_mul_f32_e32 v143, 0xbfb8aa3b, v27
	v_exp_f32_e32 v140, v140
	v_exp_f32_e32 v141, v141
	v_exp_f32_e32 v142, v142
	v_exp_f32_e32 v143, v143
	v_add_f32_e32 v140, 1.0, v140
	v_add_f32_e32 v141, 1.0, v141
	v_add_f32_e32 v142, 1.0, v142
	v_add_f32_e32 v143, 1.0, v143
	v_rcp_f32_e32 v140, v140
	v_rcp_f32_e32 v141, v141
	v_rcp_f32_e32 v142, v142
	v_rcp_f32_e32 v143, v143
	v_mul_f32_e32 v24, v24, v140
	v_mul_f32_e32 v25, v25, v141
	v_mul_f32_e32 v26, v26, v142
	v_mul_f32_e32 v27, v27, v143
	v_mul_f32_e32 v140, 0xbfb8aa3b, v28
	v_mul_f32_e32 v141, 0xbfb8aa3b, v29
	v_mul_f32_e32 v142, 0xbfb8aa3b, v30
	v_mul_f32_e32 v143, 0xbfb8aa3b, v31
	v_exp_f32_e32 v140, v140
	v_exp_f32_e32 v141, v141
	v_exp_f32_e32 v142, v142
	v_exp_f32_e32 v143, v143
	v_add_f32_e32 v140, 1.0, v140
	v_add_f32_e32 v141, 1.0, v141
	v_add_f32_e32 v142, 1.0, v142
	v_add_f32_e32 v143, 1.0, v143
	v_rcp_f32_e32 v140, v140
	v_rcp_f32_e32 v141, v141
	v_rcp_f32_e32 v142, v142
	v_rcp_f32_e32 v143, v143
	v_mul_f32_e32 v28, v28, v140
	v_mul_f32_e32 v29, v29, v141
	v_mul_f32_e32 v30, v30, v142
	v_mul_f32_e32 v31, v31, v143
	v_mul_f32_e32 v140, 0xbfb8aa3b, v36
	v_mul_f32_e32 v141, 0xbfb8aa3b, v37
	v_mul_f32_e32 v142, 0xbfb8aa3b, v38
	v_mul_f32_e32 v143, 0xbfb8aa3b, v39
	v_exp_f32_e32 v140, v140
	v_exp_f32_e32 v141, v141
	v_exp_f32_e32 v142, v142
	v_exp_f32_e32 v143, v143
	v_add_f32_e32 v140, 1.0, v140
	v_add_f32_e32 v141, 1.0, v141
	v_add_f32_e32 v142, 1.0, v142
	v_add_f32_e32 v143, 1.0, v143
	v_rcp_f32_e32 v140, v140
	v_rcp_f32_e32 v141, v141
	v_rcp_f32_e32 v142, v142
	v_rcp_f32_e32 v143, v143
	v_mul_f32_e32 v36, v36, v140
	v_mul_f32_e32 v37, v37, v141
	v_mul_f32_e32 v38, v38, v142
	v_mul_f32_e32 v39, v39, v143
	v_mul_f32_e32 v140, 0xbfb8aa3b, v40
	v_mul_f32_e32 v141, 0xbfb8aa3b, v41
	v_mul_f32_e32 v142, 0xbfb8aa3b, v42
	v_mul_f32_e32 v143, 0xbfb8aa3b, v43
	v_exp_f32_e32 v140, v140
	v_exp_f32_e32 v141, v141
	v_exp_f32_e32 v142, v142
	v_exp_f32_e32 v143, v143
	v_add_f32_e32 v140, 1.0, v140
	v_add_f32_e32 v141, 1.0, v141
	v_add_f32_e32 v142, 1.0, v142
	v_add_f32_e32 v143, 1.0, v143
	v_rcp_f32_e32 v140, v140
	v_rcp_f32_e32 v141, v141
	v_rcp_f32_e32 v142, v142
	v_rcp_f32_e32 v143, v143
	v_mul_f32_e32 v40, v40, v140
	v_mul_f32_e32 v41, v41, v141
	v_mul_f32_e32 v42, v42, v142
	v_mul_f32_e32 v43, v43, v143
	s_cmp_eq_u32 s36, 0
	s_cbranch_scc0 .Lsg_hin_st
	v_mul_f32_e32 v24, 0x3db504f3, v24
	v_mul_f32_e32 v25, 0x3db504f3, v25
	v_mul_f32_e32 v26, 0x3db504f3, v26
	v_mul_f32_e32 v27, 0x3db504f3, v27
	v_mul_f32_e32 v28, 0x3db504f3, v28
	v_mul_f32_e32 v29, 0x3db504f3, v29
	v_mul_f32_e32 v30, 0x3db504f3, v30
	v_mul_f32_e32 v31, 0x3db504f3, v31
	v_mul_f32_e32 v36, 0x3db504f3, v36
	v_mul_f32_e32 v37, 0x3db504f3, v37
	v_mul_f32_e32 v38, 0x3db504f3, v38
	v_mul_f32_e32 v39, 0x3db504f3, v39
	v_mul_f32_e32 v40, 0x3db504f3, v40
	v_mul_f32_e32 v41, 0x3db504f3, v41
	v_mul_f32_e32 v42, 0x3db504f3, v42
	v_mul_f32_e32 v43, 0x3db504f3, v43
	s_branch .Lsg_hin_st
.Lsg_hin_k:
	s_waitcnt vmcnt(0)
	v_sub_f32_e32 v128, v132, v128
	v_sub_f32_e32 v129, v133, v129
	v_sub_f32_e32 v130, v134, v130
	v_sub_f32_e32 v131, v135, v131
	v_mul_f32_e32 v128, 0x3fb8aa3b, v128
	v_mul_f32_e32 v129, 0x3fb8aa3b, v129
	v_mul_f32_e32 v130, 0x3fb8aa3b, v130
	v_mul_f32_e32 v131, 0x3fb8aa3b, v131
	v_exp_f32_e32 v128, v128
	v_exp_f32_e32 v129, v129
	v_exp_f32_e32 v130, v130
	v_exp_f32_e32 v131, v131
	v_add_f32_e32 v128, 1.0, v128
	v_add_f32_e32 v129, 1.0, v129
	v_add_f32_e32 v130, 1.0, v130
	v_add_f32_e32 v131, 1.0, v131
	v_rcp_f32_e32 v128, v128
	v_rcp_f32_e32 v129, v129
	v_rcp_f32_e32 v130, v130
	v_rcp_f32_e32 v131, v131
	v_mul_f32_e32 v140, 0x3fb8aa3b, v24
	v_mul_f32_e32 v141, 0x3fb8aa3b, v25
	v_mul_f32_e32 v142, 0x3fb8aa3b, v26
	v_mul_f32_e32 v143, 0x3fb8aa3b, v27
	v_exp_f32_e32 v140, v140
	v_exp_f32_e32 v141, v141
	v_exp_f32_e32 v142, v142
	v_exp_f32_e32 v143, v143
	v_add_f32_e32 v140, 1.0, v140
	v_add_f32_e32 v141, 1.0, v141
	v_add_f32_e32 v142, 1.0, v142
	v_add_f32_e32 v143, 1.0, v143
	v_rcp_f32_e32 v140, v140
	v_rcp_f32_e32 v141, v141
	v_rcp_f32_e32 v142, v142
	v_rcp_f32_e32 v143, v143
	v_mul_f32_e32 v24, v140, v128
	v_mul_f32_e32 v25, v141, v128
	v_mul_f32_e32 v26, v142, v128
	v_mul_f32_e32 v27, v143, v128
	v_mul_f32_e32 v140, 0x3fb8aa3b, v28
	v_mul_f32_e32 v141, 0x3fb8aa3b, v29
	v_mul_f32_e32 v142, 0x3fb8aa3b, v30
	v_mul_f32_e32 v143, 0x3fb8aa3b, v31
	v_exp_f32_e32 v140, v140
	v_exp_f32_e32 v141, v141
	v_exp_f32_e32 v142, v142
	v_exp_f32_e32 v143, v143
	v_add_f32_e32 v140, 1.0, v140
	v_add_f32_e32 v141, 1.0, v141
	v_add_f32_e32 v142, 1.0, v142
	v_add_f32_e32 v143, 1.0, v143
	v_rcp_f32_e32 v140, v140
	v_rcp_f32_e32 v141, v141
	v_rcp_f32_e32 v142, v142
	v_rcp_f32_e32 v143, v143
	v_mul_f32_e32 v28, v140, v129
	v_mul_f32_e32 v29, v141, v129
	v_mul_f32_e32 v30, v142, v129
	v_mul_f32_e32 v31, v143, v129
	v_mul_f32_e32 v140, 0x3fb8aa3b, v36
	v_mul_f32_e32 v141, 0x3fb8aa3b, v37
	v_mul_f32_e32 v142, 0x3fb8aa3b, v38
	v_mul_f32_e32 v143, 0x3fb8aa3b, v39
	v_exp_f32_e32 v140, v140
	v_exp_f32_e32 v141, v141
	v_exp_f32_e32 v142, v142
	v_exp_f32_e32 v143, v143
	v_add_f32_e32 v140, 1.0, v140
	v_add_f32_e32 v141, 1.0, v141
	v_add_f32_e32 v142, 1.0, v142
	v_add_f32_e32 v143, 1.0, v143
	v_rcp_f32_e32 v140, v140
	v_rcp_f32_e32 v141, v141
	v_rcp_f32_e32 v142, v142
	v_rcp_f32_e32 v143, v143
	v_mul_f32_e32 v36, v140, v130
	v_mul_f32_e32 v37, v141, v130
	v_mul_f32_e32 v38, v142, v130
	v_mul_f32_e32 v39, v143, v130
	v_mul_f32_e32 v140, 0x3fb8aa3b, v40
	v_mul_f32_e32 v141, 0x3fb8aa3b, v41
	v_mul_f32_e32 v142, 0x3fb8aa3b, v42
	v_mul_f32_e32 v143, 0x3fb8aa3b, v43
	v_exp_f32_e32 v140, v140
	v_exp_f32_e32 v141, v141
	v_exp_f32_e32 v142, v142
	v_exp_f32_e32 v143, v143
	v_add_f32_e32 v140, 1.0, v140
	v_add_f32_e32 v141, 1.0, v141
	v_add_f32_e32 v142, 1.0, v142
	v_add_f32_e32 v143, 1.0, v143
	v_rcp_f32_e32 v140, v140
	v_rcp_f32_e32 v141, v141
	v_rcp_f32_e32 v142, v142
	v_rcp_f32_e32 v143, v143
	v_mul_f32_e32 v40, v140, v131
	v_mul_f32_e32 v41, v141, v131
	v_mul_f32_e32 v42, v142, v131
	v_mul_f32_e32 v43, v143, v131
.Lsg_hin_st:
	s_nop 7
	v_bfe_u32 v140, v24, 16, 1
	v_bfe_u32 v141, v25, 16, 1
	v_bfe_u32 v142, v26, 16, 1
	v_bfe_u32 v143, v27, 16, 1
	v_add3_u32 v140, v24, v140, s3
	v_add3_u32 v141, v25, v141, s3
	v_add3_u32 v142, v26, v142, s3
	v_add3_u32 v143, v27, v143, s3
	global_store_short_d16_hi v[136:137], v140, off offset:0
	global_store_short_d16_hi v[136:137], v141, off offset:2048
	global_store_short_d16_hi v[138:139], v142, off offset:0
	global_store_short_d16_hi v[138:139], v143, off offset:2048
	v_bfe_u32 v140, v28, 16, 1
	v_bfe_u32 v141, v29, 16, 1
	v_bfe_u32 v142, v30, 16, 1
	v_bfe_u32 v143, v31, 16, 1
	v_add3_u32 v140, v28, v140, s3
	v_add3_u32 v141, v29, v141, s3
	v_add3_u32 v142, v30, v142, s3
	v_add3_u32 v143, v31, v143, s3
	global_store_short_d16_hi v[136:137], v140, off offset:32
	global_store_short_d16_hi v[136:137], v141, off offset:2080
	global_store_short_d16_hi v[138:139], v142, off offset:32
	global_store_short_d16_hi v[138:139], v143, off offset:2080
	v_bfe_u32 v140, v36, 16, 1
	v_bfe_u32 v141, v37, 16, 1
	v_bfe_u32 v142, v38, 16, 1
	v_bfe_u32 v143, v39, 16, 1
	v_add3_u32 v140, v36, v140, s3
	v_add3_u32 v141, v37, v141, s3
	v_add3_u32 v142, v38, v142, s3
	v_add3_u32 v143, v39, v143, s3
	global_store_short_d16_hi v[136:137], v140, off offset:64
	global_store_short_d16_hi v[136:137], v141, off offset:2112
	global_store_short_d16_hi v[138:139], v142, off offset:64
	global_store_short_d16_hi v[138:139], v143, off offset:2112
	v_bfe_u32 v140, v40, 16, 1
	v_bfe_u32 v141, v41, 16, 1
	v_bfe_u32 v142, v42, 16, 1
	v_bfe_u32 v143, v43, 16, 1
	v_add3_u32 v140, v40, v140, s3
	v_add3_u32 v141, v41, v141, s3
	v_add3_u32 v142, v42, v142, s3
	v_add3_u32 v143, v43, v143, s3
	global_store_short_d16_hi v[136:137], v140, off offset:96
	global_store_short_d16_hi v[136:137], v141, off offset:2144
	global_store_short_d16_hi v[138:139], v142, off offset:96
	global_store_short_d16_hi v[138:139], v143, off offset:2144
	s_add_i32 s35, s35, s56
	s_cmpk_lt_i32 s35, 0x100
	s_cbranch_scc1 .Lsg_hin_tile
